# GEMM K loops: first fragment reads reordered (A0,B0..B3,A1) with per-MFMA counted lgkmcnt waits so MFMAs start as soon as their own fragments land
# baseline (speedup 1.0000x reference)
.Lgq_c:
	ds_read_b128 v[122:125], v112
	ds_read_b128 v[114:117], v188 offset:16384
	ds_read_b128 v[118:121], v188 offset:16896
	ds_read_b128 v[156:159], v188 offset:20480
	ds_read_b128 v[160:163], v188 offset:20992
	ds_read_b128 v[126:129], v112 offset:2048
	s_waitcnt lgkmcnt(4)
	v_mfma_f32_16x16x32_bf16 v[66:69], v[114:117], v[122:125], v[66:69]
	global_load_dwordx4 v[62:65], v216, s[0:1] offset:256
	s_waitcnt lgkmcnt(3)
	v_mfma_f32_16x16x32_bf16 v[58:61], v[118:121], v[122:125], v[58:61]
	s_waitcnt vmcnt(8)
	ds_write_b128 v110, v[224:227] offset:32768
	s_waitcnt lgkmcnt(3)
	v_mfma_f32_16x16x32_bf16 v[54:57], v[156:159], v[122:125], v[54:57]
	s_waitcnt lgkmcnt(2)
	v_mfma_f32_16x16x32_bf16 v[50:53], v[160:163], v[122:125], v[50:53]
	global_load_dwordx4 v[70:73], v217, s[0:1] offset:256
	s_waitcnt lgkmcnt(1)
	v_mfma_f32_16x16x32_bf16 v[46:49], v[114:117], v[126:129], v[46:49]
	ds_read_b128 v[180:183], v112 offset:4096
	ds_read_b128 v[184:187], v112 offset:6144
	v_mfma_f32_16x16x32_bf16 v[42:45], v[118:121], v[126:129], v[42:45]
	s_waitcnt vmcnt(8)
	ds_write_b128 v110, v[228:231] offset:36864
	v_mfma_f32_16x16x32_bf16 v[38:41], v[156:159], v[126:129], v[38:41]
	global_load_dwordx4 v[74:77], v218, s[0:1] offset:256
	v_mfma_f32_16x16x32_bf16 v[34:37], v[160:163], v[126:129], v[34:37]
	s_waitcnt lgkmcnt(2)
	v_mfma_f32_16x16x32_bf16 v[30:33], v[114:117], v[180:183], v[30:33]
	ds_read_b128 v[164:167], v189 offset:16384
	ds_read_b128 v[168:171], v189 offset:16896
	v_mfma_f32_16x16x32_bf16 v[26:29], v[118:121], v[180:183], v[26:29]
	global_load_dwordx4 v[78:81], v219, s[0:1] offset:256
	v_mfma_f32_16x16x32_bf16 v[22:25], v[156:159], v[180:183], v[22:25]
	ds_read_b128 v[172:175], v189 offset:20480
	ds_read_b128 v[176:179], v189 offset:20992
	v_mfma_f32_16x16x32_bf16 v[18:21], v[160:163], v[180:183], v[18:21]
	s_waitcnt vmcnt(9)
	ds_write_b128 v110, v[232:235] offset:40960
	s_waitcnt lgkmcnt(6)
	v_mfma_f32_16x16x32_bf16 v[14:17], v[114:117], v[184:187], v[14:17]
	ds_read_b128 v[122:125], v113
	ds_read_b128 v[126:129], v113 offset:2048
	v_mfma_f32_16x16x32_bf16 v[10:13], v[118:121], v[184:187], v[10:13]
	global_load_dwordx4 v[82:85], v216, s[6:7] offset:256
	v_mfma_f32_16x16x32_bf16 v[6:9], v[156:159], v[184:187], v[6:9]
	s_waitcnt vmcnt(9)
	ds_write_b128 v110, v[236:239] offset:45056
	v_mfma_f32_16x16x32_bf16 v[2:5], v[160:163], v[184:187], v[2:5]
	s_waitcnt lgkmcnt(2)
	v_mfma_f32_16x16x32_bf16 v[66:69], v[164:167], v[122:125], v[66:69]
	global_load_dwordx4 v[86:89], v217, s[6:7] offset:256
	v_mfma_f32_16x16x32_bf16 v[58:61], v[168:171], v[122:125], v[58:61]
	s_waitcnt vmcnt(9)
	ds_write_b128 v190, v[240:243] offset:49168
	v_mfma_f32_16x16x32_bf16 v[54:57], v[172:175], v[122:125], v[54:57]
	v_mfma_f32_16x16x32_bf16 v[50:53], v[176:179], v[122:125], v[50:53]
	global_load_dwordx4 v[90:93], v218, s[6:7] offset:256
	s_waitcnt lgkmcnt(2)
	v_mfma_f32_16x16x32_bf16 v[46:49], v[164:167], v[126:129], v[46:49]
	ds_read_b128 v[180:183], v113 offset:4096
	ds_read_b128 v[184:187], v113 offset:6144
	v_mfma_f32_16x16x32_bf16 v[42:45], v[168:171], v[126:129], v[42:45]
	s_waitcnt vmcnt(9)
	ds_write_b128 v190, v[244:247] offset:53264
	v_mfma_f32_16x16x32_bf16 v[38:41], v[172:175], v[126:129], v[38:41]
	global_load_dwordx4 v[94:97], v219, s[6:7] offset:256
	v_mfma_f32_16x16x32_bf16 v[34:37], v[176:179], v[126:129], v[34:37]
	s_waitcnt lgkmcnt(2)
	v_mfma_f32_16x16x32_bf16 v[30:33], v[164:167], v[180:183], v[30:33]
	s_waitcnt vmcnt(9)
	ds_write_b128 v190, v[248:251] offset:57360
	v_mfma_f32_16x16x32_bf16 v[26:29], v[168:171], v[180:183], v[26:29]
	v_mfma_f32_16x16x32_bf16 v[22:25], v[172:175], v[180:183], v[22:25]
	v_mfma_f32_16x16x32_bf16 v[18:21], v[176:179], v[180:183], v[18:21]
	s_waitcnt vmcnt(8)
	ds_write_b128 v190, v[252:255] offset:61456
	s_waitcnt lgkmcnt(3)
	v_mfma_f32_16x16x32_bf16 v[14:17], v[164:167], v[184:187], v[14:17]
	v_mfma_f32_16x16x32_bf16 v[10:13], v[168:171], v[184:187], v[10:13]
	v_mfma_f32_16x16x32_bf16 v[6:9], v[172:175], v[184:187], v[6:9]
	v_mfma_f32_16x16x32_bf16 v[2:5], v[176:179], v[184:187], v[2:5]
	s_waitcnt lgkmcnt(0)
	s_barrier
	s_add_u32 s0, s0, 0x80
	s_addc_u32 s1, s1, 0
	s_add_u32 s6, s6, 0x80
	s_addc_u32 s7, s7, 0
	ds_read_b128 v[122:125], v112 offset:32768
	ds_read_b128 v[114:117], v188 offset:49168
	ds_read_b128 v[118:121], v188 offset:49680
	ds_read_b128 v[156:159], v188 offset:53264
	ds_read_b128 v[160:163], v188 offset:53776
	ds_read_b128 v[126:129], v112 offset:34816
	s_waitcnt lgkmcnt(4)
	v_mfma_f32_16x16x32_bf16 v[66:69], v[114:117], v[122:125], v[66:69]
	global_load_dwordx4 v[224:227], v216, s[0:1] offset:256
	s_waitcnt lgkmcnt(3)
	v_mfma_f32_16x16x32_bf16 v[58:61], v[118:121], v[122:125], v[58:61]
	s_waitcnt vmcnt(8)
	ds_write_b128 v110, v[62:65]
	s_waitcnt lgkmcnt(3)
	v_mfma_f32_16x16x32_bf16 v[54:57], v[156:159], v[122:125], v[54:57]
	s_waitcnt lgkmcnt(2)
	v_mfma_f32_16x16x32_bf16 v[50:53], v[160:163], v[122:125], v[50:53]
	global_load_dwordx4 v[228:231], v217, s[0:1] offset:256
	s_waitcnt lgkmcnt(1)
	v_mfma_f32_16x16x32_bf16 v[46:49], v[114:117], v[126:129], v[46:49]
	ds_read_b128 v[180:183], v112 offset:36864
	ds_read_b128 v[184:187], v112 offset:38912
	v_mfma_f32_16x16x32_bf16 v[42:45], v[118:121], v[126:129], v[42:45]
	s_waitcnt vmcnt(8)
	ds_write_b128 v110, v[70:73] offset:4096
	v_mfma_f32_16x16x32_bf16 v[38:41], v[156:159], v[126:129], v[38:41]
	global_load_dwordx4 v[232:235], v218, s[0:1] offset:256
	v_mfma_f32_16x16x32_bf16 v[34:37], v[160:163], v[126:129], v[34:37]
	s_waitcnt lgkmcnt(2)
	v_mfma_f32_16x16x32_bf16 v[30:33], v[114:117], v[180:183], v[30:33]
	ds_read_b128 v[164:167], v189 offset:49168
	ds_read_b128 v[168:171], v189 offset:49680
	v_mfma_f32_16x16x32_bf16 v[26:29], v[118:121], v[180:183], v[26:29]
	global_load_dwordx4 v[236:239], v219, s[0:1] offset:256
	v_mfma_f32_16x16x32_bf16 v[22:25], v[156:159], v[180:183], v[22:25]
	ds_read_b128 v[172:175], v189 offset:53264
	ds_read_b128 v[176:179], v189 offset:53776
	v_mfma_f32_16x16x32_bf16 v[18:21], v[160:163], v[180:183], v[18:21]
	s_waitcnt vmcnt(9)
	ds_write_b128 v110, v[74:77] offset:8192
	s_waitcnt lgkmcnt(6)
	v_mfma_f32_16x16x32_bf16 v[14:17], v[114:117], v[184:187], v[14:17]
	ds_read_b128 v[122:125], v113 offset:32768
	ds_read_b128 v[126:129], v113 offset:34816
	v_mfma_f32_16x16x32_bf16 v[10:13], v[118:121], v[184:187], v[10:13]
	global_load_dwordx4 v[240:243], v216, s[6:7] offset:256
	v_mfma_f32_16x16x32_bf16 v[6:9], v[156:159], v[184:187], v[6:9]
	s_waitcnt vmcnt(9)
	ds_write_b128 v110, v[78:81] offset:12288
	v_mfma_f32_16x16x32_bf16 v[2:5], v[160:163], v[184:187], v[2:5]
	s_waitcnt lgkmcnt(2)
	v_mfma_f32_16x16x32_bf16 v[66:69], v[164:167], v[122:125], v[66:69]
	global_load_dwordx4 v[244:247], v217, s[6:7] offset:256
	v_mfma_f32_16x16x32_bf16 v[58:61], v[168:171], v[122:125], v[58:61]
	s_waitcnt vmcnt(9)
	ds_write_b128 v190, v[82:85] offset:16384
	v_mfma_f32_16x16x32_bf16 v[54:57], v[172:175], v[122:125], v[54:57]
	v_mfma_f32_16x16x32_bf16 v[50:53], v[176:179], v[122:125], v[50:53]
	global_load_dwordx4 v[248:251], v218, s[6:7] offset:256
	s_waitcnt lgkmcnt(2)
	v_mfma_f32_16x16x32_bf16 v[46:49], v[164:167], v[126:129], v[46:49]
	ds_read_b128 v[180:183], v113 offset:36864
	ds_read_b128 v[184:187], v113 offset:38912
	v_mfma_f32_16x16x32_bf16 v[42:45], v[168:171], v[126:129], v[42:45]
	s_waitcnt vmcnt(9)
	ds_write_b128 v190, v[86:89] offset:20480
	v_mfma_f32_16x16x32_bf16 v[38:41], v[172:175], v[126:129], v[38:41]
	global_load_dwordx4 v[252:255], v219, s[6:7] offset:256
	v_mfma_f32_16x16x32_bf16 v[34:37], v[176:179], v[126:129], v[34:37]
	s_waitcnt lgkmcnt(2)
	v_mfma_f32_16x16x32_bf16 v[30:33], v[164:167], v[180:183], v[30:33]
	s_waitcnt vmcnt(9)
	ds_write_b128 v190, v[90:93] offset:24576
	v_mfma_f32_16x16x32_bf16 v[26:29], v[168:171], v[180:183], v[26:29]
	v_mfma_f32_16x16x32_bf16 v[22:25], v[172:175], v[180:183], v[22:25]
	v_mfma_f32_16x16x32_bf16 v[18:21], v[176:179], v[180:183], v[18:21]
	s_waitcnt vmcnt(8)
	ds_write_b128 v190, v[94:97] offset:28672
	s_waitcnt lgkmcnt(3)
	v_mfma_f32_16x16x32_bf16 v[14:17], v[164:167], v[184:187], v[14:17]
	v_mfma_f32_16x16x32_bf16 v[10:13], v[168:171], v[184:187], v[10:13]
	v_mfma_f32_16x16x32_bf16 v[6:9], v[172:175], v[184:187], v[6:9]
	v_mfma_f32_16x16x32_bf16 v[2:5], v[176:179], v[184:187], v[2:5]
	s_waitcnt lgkmcnt(0)
	s_barrier
	s_add_u32 s0, s0, 0x80
	s_addc_u32 s1, s1, 0
	s_add_u32 s6, s6, 0x80
	s_addc_u32 s7, s7, 0
	s_sub_i32 vcc_lo, vcc_lo, 1
	s_cmp_lg_u32 vcc_lo, 0
	s_cbranch_scc1 .Lgq_c
	ds_read_b128 v[122:125], v112
	ds_read_b128 v[114:117], v188 offset:16384
	ds_read_b128 v[118:121], v188 offset:16896
	ds_read_b128 v[156:159], v188 offset:20480
	ds_read_b128 v[160:163], v188 offset:20992
	ds_read_b128 v[126:129], v112 offset:2048
	s_waitcnt lgkmcnt(4)
	v_mfma_f32_16x16x32_bf16 v[66:69], v[114:117], v[122:125], v[66:69]
	s_waitcnt lgkmcnt(3)
	v_mfma_f32_16x16x32_bf16 v[58:61], v[118:121], v[122:125], v[58:61]
	s_waitcnt vmcnt(7)
	ds_write_b128 v110, v[224:227] offset:32768
	s_waitcnt lgkmcnt(3)
	v_mfma_f32_16x16x32_bf16 v[54:57], v[156:159], v[122:125], v[54:57]
	s_waitcnt lgkmcnt(2)
	v_mfma_f32_16x16x32_bf16 v[50:53], v[160:163], v[122:125], v[50:53]
	s_waitcnt lgkmcnt(1)
	v_mfma_f32_16x16x32_bf16 v[46:49], v[114:117], v[126:129], v[46:49]
	ds_read_b128 v[180:183], v112 offset:4096
	ds_read_b128 v[184:187], v112 offset:6144
	v_mfma_f32_16x16x32_bf16 v[42:45], v[118:121], v[126:129], v[42:45]
	s_waitcnt vmcnt(6)
	ds_write_b128 v110, v[228:231] offset:36864
	v_mfma_f32_16x16x32_bf16 v[38:41], v[156:159], v[126:129], v[38:41]
	v_mfma_f32_16x16x32_bf16 v[34:37], v[160:163], v[126:129], v[34:37]
	s_waitcnt lgkmcnt(2)
	v_mfma_f32_16x16x32_bf16 v[30:33], v[114:117], v[180:183], v[30:33]
	ds_read_b128 v[164:167], v189 offset:16384
	ds_read_b128 v[168:171], v189 offset:16896
	v_mfma_f32_16x16x32_bf16 v[26:29], v[118:121], v[180:183], v[26:29]
	v_mfma_f32_16x16x32_bf16 v[22:25], v[156:159], v[180:183], v[22:25]
	ds_read_b128 v[172:175], v189 offset:20480
	ds_read_b128 v[176:179], v189 offset:20992
	v_mfma_f32_16x16x32_bf16 v[18:21], v[160:163], v[180:183], v[18:21]
	s_waitcnt vmcnt(5)
	ds_write_b128 v110, v[232:235] offset:40960
	s_waitcnt lgkmcnt(6)
	v_mfma_f32_16x16x32_bf16 v[14:17], v[114:117], v[184:187], v[14:17]
	ds_read_b128 v[122:125], v113
	ds_read_b128 v[126:129], v113 offset:2048
	v_mfma_f32_16x16x32_bf16 v[10:13], v[118:121], v[184:187], v[10:13]
	v_mfma_f32_16x16x32_bf16 v[6:9], v[156:159], v[184:187], v[6:9]
	s_waitcnt vmcnt(4)
	ds_write_b128 v110, v[236:239] offset:45056
	v_mfma_f32_16x16x32_bf16 v[2:5], v[160:163], v[184:187], v[2:5]
	s_waitcnt lgkmcnt(2)
	v_mfma_f32_16x16x32_bf16 v[66:69], v[164:167], v[122:125], v[66:69]
	v_mfma_f32_16x16x32_bf16 v[58:61], v[168:171], v[122:125], v[58:61]
	s_waitcnt vmcnt(3)
	ds_write_b128 v190, v[240:243] offset:49168
	v_mfma_f32_16x16x32_bf16 v[54:57], v[172:175], v[122:125], v[54:57]
	v_mfma_f32_16x16x32_bf16 v[50:53], v[176:179], v[122:125], v[50:53]
	s_waitcnt lgkmcnt(2)
	v_mfma_f32_16x16x32_bf16 v[46:49], v[164:167], v[126:129], v[46:49]
	ds_read_b128 v[180:183], v113 offset:4096
	ds_read_b128 v[184:187], v113 offset:6144
	v_mfma_f32_16x16x32_bf16 v[42:45], v[168:171], v[126:129], v[42:45]
	s_waitcnt vmcnt(2)
	ds_write_b128 v190, v[244:247] offset:53264
	v_mfma_f32_16x16x32_bf16 v[38:41], v[172:175], v[126:129], v[38:41]
	v_mfma_f32_16x16x32_bf16 v[34:37], v[176:179], v[126:129], v[34:37]
	s_waitcnt lgkmcnt(2)
	v_mfma_f32_16x16x32_bf16 v[30:33], v[164:167], v[180:183], v[30:33]
	s_waitcnt vmcnt(1)
	ds_write_b128 v190, v[248:251] offset:57360
	v_mfma_f32_16x16x32_bf16 v[26:29], v[168:171], v[180:183], v[26:29]
	v_mfma_f32_16x16x32_bf16 v[22:25], v[172:175], v[180:183], v[22:25]
	v_mfma_f32_16x16x32_bf16 v[18:21], v[176:179], v[180:183], v[18:21]
	s_waitcnt vmcnt(0)
	ds_write_b128 v190, v[252:255] offset:61456
	s_waitcnt lgkmcnt(3)
	v_mfma_f32_16x16x32_bf16 v[14:17], v[164:167], v[184:187], v[14:17]
	v_mfma_f32_16x16x32_bf16 v[10:13], v[168:171], v[184:187], v[10:13]
	v_mfma_f32_16x16x32_bf16 v[6:9], v[172:175], v[184:187], v[6:9]
	v_mfma_f32_16x16x32_bf16 v[2:5], v[176:179], v[184:187], v[2:5]
	s_waitcnt lgkmcnt(0)
	s_barrier
	ds_read_b128 v[122:125], v112 offset:32768
	ds_read_b128 v[114:117], v188 offset:49168
	ds_read_b128 v[118:121], v188 offset:49680
	ds_read_b128 v[156:159], v188 offset:53264
	ds_read_b128 v[160:163], v188 offset:53776
	ds_read_b128 v[126:129], v112 offset:34816
	s_waitcnt lgkmcnt(4)
	v_mfma_f32_16x16x32_bf16 v[66:69], v[114:117], v[122:125], v[66:69]
	s_waitcnt lgkmcnt(3)
	v_mfma_f32_16x16x32_bf16 v[58:61], v[118:121], v[122:125], v[58:61]
	s_waitcnt lgkmcnt(2)
	v_mfma_f32_16x16x32_bf16 v[54:57], v[156:159], v[122:125], v[54:57]
	s_waitcnt lgkmcnt(1)
	v_mfma_f32_16x16x32_bf16 v[50:53], v[160:163], v[122:125], v[50:53]
	s_waitcnt lgkmcnt(0)
	v_mfma_f32_16x16x32_bf16 v[46:49], v[114:117], v[126:129], v[46:49]
	ds_read_b128 v[180:183], v112 offset:36864
	ds_read_b128 v[184:187], v112 offset:38912
	v_mfma_f32_16x16x32_bf16 v[42:45], v[118:121], v[126:129], v[42:45]
	v_mfma_f32_16x16x32_bf16 v[38:41], v[156:159], v[126:129], v[38:41]
	v_mfma_f32_16x16x32_bf16 v[34:37], v[160:163], v[126:129], v[34:37]
	s_waitcnt lgkmcnt(1)
	v_mfma_f32_16x16x32_bf16 v[30:33], v[114:117], v[180:183], v[30:33]
	ds_read_b128 v[164:167], v189 offset:49168
	ds_read_b128 v[168:171], v189 offset:49680
	v_mfma_f32_16x16x32_bf16 v[26:29], v[118:121], v[180:183], v[26:29]
	v_mfma_f32_16x16x32_bf16 v[22:25], v[156:159], v[180:183], v[22:25]
	ds_read_b128 v[172:175], v189 offset:53264
	ds_read_b128 v[176:179], v189 offset:53776
	v_mfma_f32_16x16x32_bf16 v[18:21], v[160:163], v[180:183], v[18:21]
	s_waitcnt lgkmcnt(4)
	v_mfma_f32_16x16x32_bf16 v[14:17], v[114:117], v[184:187], v[14:17]
	ds_read_b128 v[122:125], v113 offset:32768
	ds_read_b128 v[126:129], v113 offset:34816
	v_mfma_f32_16x16x32_bf16 v[10:13], v[118:121], v[184:187], v[10:13]
	v_mfma_f32_16x16x32_bf16 v[6:9], v[156:159], v[184:187], v[6:9]
	v_mfma_f32_16x16x32_bf16 v[2:5], v[160:163], v[184:187], v[2:5]
	s_waitcnt lgkmcnt(1)
	v_mfma_f32_16x16x32_bf16 v[66:69], v[164:167], v[122:125], v[66:69]
	v_mfma_f32_16x16x32_bf16 v[58:61], v[168:171], v[122:125], v[58:61]
	v_mfma_f32_16x16x32_bf16 v[54:57], v[172:175], v[122:125], v[54:57]
	v_mfma_f32_16x16x32_bf16 v[50:53], v[176:179], v[122:125], v[50:53]
	s_waitcnt lgkmcnt(0)
	v_mfma_f32_16x16x32_bf16 v[46:49], v[164:167], v[126:129], v[46:49]
	ds_read_b128 v[180:183], v113 offset:36864
	ds_read_b128 v[184:187], v113 offset:38912
	v_mfma_f32_16x16x32_bf16 v[42:45], v[168:171], v[126:129], v[42:45]
	v_mfma_f32_16x16x32_bf16 v[38:41], v[172:175], v[126:129], v[38:41]
	v_mfma_f32_16x16x32_bf16 v[34:37], v[176:179], v[126:129], v[34:37]
	s_waitcnt lgkmcnt(1)
	v_mfma_f32_16x16x32_bf16 v[30:33], v[164:167], v[180:183], v[30:33]
	v_mfma_f32_16x16x32_bf16 v[26:29], v[168:171], v[180:183], v[26:29]
	v_mfma_f32_16x16x32_bf16 v[22:25], v[172:175], v[180:183], v[22:25]
	v_mfma_f32_16x16x32_bf16 v[18:21], v[176:179], v[180:183], v[18:21]
	s_waitcnt lgkmcnt(0)
	v_mfma_f32_16x16x32_bf16 v[14:17], v[164:167], v[184:187], v[14:17]
	v_mfma_f32_16x16x32_bf16 v[10:13], v[168:171], v[184:187], v[10:13]
	v_mfma_f32_16x16x32_bf16 v[6:9], v[172:175], v[184:187], v[6:9]
	v_mfma_f32_16x16x32_bf16 v[2:5], v[176:179], v[184:187], v[2:5]
	s_barrier

.Lgq_h:
	ds_read_b128 v[82:85], v71
	ds_read_b128 v[74:77], v188 offset:16384
	ds_read_b128 v[78:81], v188 offset:16896
	ds_read_b128 v[90:93], v188 offset:20480
	ds_read_b128 v[94:97], v188 offset:20992
	ds_read_b128 v[86:89], v71 offset:2048
	s_waitcnt lgkmcnt(4)
	v_mfma_f32_16x16x32_bf16 v[30:33], v[74:77], v[82:85], v[30:33]
	ds_read_b128 v[164:167], v189 offset:16384
	ds_read_b128 v[168:171], v189 offset:16896
	global_load_dwordx4 v[34:37], v216, s[0:1] offset:256
	s_waitcnt lgkmcnt(5)
	v_mfma_f32_16x16x32_bf16 v[26:29], v[78:81], v[82:85], v[26:29]
	s_waitcnt vmcnt(6)
	ds_write_b128 v69, v[224:227] offset:32768
	s_waitcnt lgkmcnt(5)
	v_mfma_f32_16x16x32_bf16 v[22:25], v[90:93], v[82:85], v[22:25]
	ds_read_b128 v[172:175], v189 offset:20480
	ds_read_b128 v[176:179], v189 offset:20992
	s_waitcnt lgkmcnt(6)
	v_mfma_f32_16x16x32_bf16 v[18:21], v[94:97], v[82:85], v[18:21]
	global_load_dwordx4 v[46:49], v217, s[0:1] offset:256
	s_waitcnt lgkmcnt(5)
	v_mfma_f32_16x16x32_bf16 v[14:17], v[74:77], v[86:89], v[14:17]
	ds_read_b128 v[180:183], v72
	ds_read_b128 v[184:187], v72 offset:2048
	s_waitcnt vmcnt(6)
	ds_write_b128 v69, v[228:231] offset:36864
	v_mfma_f32_16x16x32_bf16 v[10:13], v[78:81], v[86:89], v[10:13]
	global_load_dwordx4 v[38:41], v216, s[6:7] offset:256
	v_mfma_f32_16x16x32_bf16 v[6:9], v[90:93], v[86:89], v[6:9]
	s_waitcnt vmcnt(6)
	ds_write_b128 v190, v[232:235] offset:49168
	v_mfma_f32_16x16x32_bf16 v[2:5], v[94:97], v[86:89], v[2:5]
	s_waitcnt lgkmcnt(3)
	v_mfma_f32_16x16x32_bf16 v[30:33], v[164:167], v[180:183], v[30:33]
	global_load_dwordx4 v[42:45], v217, s[6:7] offset:256
	v_mfma_f32_16x16x32_bf16 v[26:29], v[168:171], v[180:183], v[26:29]
	s_waitcnt vmcnt(6)
	ds_write_b128 v190, v[236:239] offset:53264
	v_mfma_f32_16x16x32_bf16 v[22:25], v[172:175], v[180:183], v[22:25]
	global_load_dwordx4 v[50:53], v218, s[6:7] offset:256
	v_mfma_f32_16x16x32_bf16 v[18:21], v[176:179], v[180:183], v[18:21]
	s_waitcnt vmcnt(6)
	ds_write_b128 v190, v[240:243] offset:57360
	s_waitcnt lgkmcnt(4)
	v_mfma_f32_16x16x32_bf16 v[14:17], v[164:167], v[184:187], v[14:17]
	global_load_dwordx4 v[54:57], v219, s[6:7] offset:256
	v_mfma_f32_16x16x32_bf16 v[10:13], v[168:171], v[184:187], v[10:13]
	s_waitcnt vmcnt(6)
	ds_write_b128 v190, v[244:247] offset:61456
	v_mfma_f32_16x16x32_bf16 v[6:9], v[172:175], v[184:187], v[6:9]
	v_mfma_f32_16x16x32_bf16 v[2:5], v[176:179], v[184:187], v[2:5]
	s_waitcnt lgkmcnt(0)
	s_barrier
	s_add_u32 s0, s0, 0x80
	s_addc_u32 s1, s1, 0
	s_add_u32 s6, s6, 0x80
	s_addc_u32 s7, s7, 0
	ds_read_b128 v[82:85], v71 offset:32768
	ds_read_b128 v[74:77], v188 offset:49168
	ds_read_b128 v[78:81], v188 offset:49680
	ds_read_b128 v[90:93], v188 offset:53264
	ds_read_b128 v[94:97], v188 offset:53776
	ds_read_b128 v[86:89], v71 offset:34816
	s_waitcnt lgkmcnt(4)
	v_mfma_f32_16x16x32_bf16 v[30:33], v[74:77], v[82:85], v[30:33]
	ds_read_b128 v[164:167], v189 offset:49168
	ds_read_b128 v[168:171], v189 offset:49680
	global_load_dwordx4 v[224:227], v216, s[0:1] offset:256
	s_waitcnt lgkmcnt(5)
	v_mfma_f32_16x16x32_bf16 v[26:29], v[78:81], v[82:85], v[26:29]
	s_waitcnt vmcnt(6)
	ds_write_b128 v69, v[34:37]
	s_waitcnt lgkmcnt(5)
	v_mfma_f32_16x16x32_bf16 v[22:25], v[90:93], v[82:85], v[22:25]
	ds_read_b128 v[172:175], v189 offset:53264
	ds_read_b128 v[176:179], v189 offset:53776
	s_waitcnt lgkmcnt(6)
	v_mfma_f32_16x16x32_bf16 v[18:21], v[94:97], v[82:85], v[18:21]
	global_load_dwordx4 v[228:231], v217, s[0:1] offset:256
	s_waitcnt lgkmcnt(5)
	v_mfma_f32_16x16x32_bf16 v[14:17], v[74:77], v[86:89], v[14:17]
	ds_read_b128 v[180:183], v72 offset:32768
	ds_read_b128 v[184:187], v72 offset:34816
	s_waitcnt vmcnt(6)
	ds_write_b128 v69, v[46:49] offset:4096
	v_mfma_f32_16x16x32_bf16 v[10:13], v[78:81], v[86:89], v[10:13]
	global_load_dwordx4 v[232:235], v216, s[6:7] offset:256
	v_mfma_f32_16x16x32_bf16 v[6:9], v[90:93], v[86:89], v[6:9]
	s_waitcnt vmcnt(6)
	ds_write_b128 v190, v[38:41] offset:16384
	v_mfma_f32_16x16x32_bf16 v[2:5], v[94:97], v[86:89], v[2:5]
	s_waitcnt lgkmcnt(3)
	v_mfma_f32_16x16x32_bf16 v[30:33], v[164:167], v[180:183], v[30:33]
	global_load_dwordx4 v[236:239], v217, s[6:7] offset:256
	v_mfma_f32_16x16x32_bf16 v[26:29], v[168:171], v[180:183], v[26:29]
	s_waitcnt vmcnt(6)
	ds_write_b128 v190, v[42:45] offset:20480
	v_mfma_f32_16x16x32_bf16 v[22:25], v[172:175], v[180:183], v[22:25]
	global_load_dwordx4 v[240:243], v218, s[6:7] offset:256
	v_mfma_f32_16x16x32_bf16 v[18:21], v[176:179], v[180:183], v[18:21]
	s_waitcnt vmcnt(6)
	ds_write_b128 v190, v[50:53] offset:24576
	s_waitcnt lgkmcnt(4)
	v_mfma_f32_16x16x32_bf16 v[14:17], v[164:167], v[184:187], v[14:17]
	global_load_dwordx4 v[244:247], v219, s[6:7] offset:256
	v_mfma_f32_16x16x32_bf16 v[10:13], v[168:171], v[184:187], v[10:13]
	s_waitcnt vmcnt(6)
	ds_write_b128 v190, v[54:57] offset:28672
	v_mfma_f32_16x16x32_bf16 v[6:9], v[172:175], v[184:187], v[6:9]
	v_mfma_f32_16x16x32_bf16 v[2:5], v[176:179], v[184:187], v[2:5]
	s_waitcnt lgkmcnt(0)
	s_barrier
	s_add_u32 s0, s0, 0x80
	s_addc_u32 s1, s1, 0
	s_add_u32 s6, s6, 0x80
	s_addc_u32 s7, s7, 0
	s_sub_i32 vcc_lo, vcc_lo, 1
	s_cmp_lg_u32 vcc_lo, 0
	s_cbranch_scc1 .Lgq_h
	ds_read_b128 v[82:85], v71
	ds_read_b128 v[74:77], v188 offset:16384
	ds_read_b128 v[78:81], v188 offset:16896
	ds_read_b128 v[90:93], v188 offset:20480
	ds_read_b128 v[94:97], v188 offset:20992
	ds_read_b128 v[86:89], v71 offset:2048
	s_waitcnt lgkmcnt(4)
	v_mfma_f32_16x16x32_bf16 v[30:33], v[74:77], v[82:85], v[30:33]
	ds_read_b128 v[164:167], v189 offset:16384
	ds_read_b128 v[168:171], v189 offset:16896
	s_waitcnt lgkmcnt(5)
	v_mfma_f32_16x16x32_bf16 v[26:29], v[78:81], v[82:85], v[26:29]
	s_waitcnt vmcnt(5)
	ds_write_b128 v69, v[224:227] offset:32768
	s_waitcnt lgkmcnt(5)
	v_mfma_f32_16x16x32_bf16 v[22:25], v[90:93], v[82:85], v[22:25]
	ds_read_b128 v[172:175], v189 offset:20480
	ds_read_b128 v[176:179], v189 offset:20992
	s_waitcnt lgkmcnt(6)
	v_mfma_f32_16x16x32_bf16 v[18:21], v[94:97], v[82:85], v[18:21]
	s_waitcnt lgkmcnt(5)
	v_mfma_f32_16x16x32_bf16 v[14:17], v[74:77], v[86:89], v[14:17]
	ds_read_b128 v[180:183], v72
	ds_read_b128 v[184:187], v72 offset:2048
	s_waitcnt vmcnt(4)
	ds_write_b128 v69, v[228:231] offset:36864
	v_mfma_f32_16x16x32_bf16 v[10:13], v[78:81], v[86:89], v[10:13]
	v_mfma_f32_16x16x32_bf16 v[6:9], v[90:93], v[86:89], v[6:9]
	s_waitcnt vmcnt(3)
	ds_write_b128 v190, v[232:235] offset:49168
	v_mfma_f32_16x16x32_bf16 v[2:5], v[94:97], v[86:89], v[2:5]
	s_waitcnt lgkmcnt(3)
	v_mfma_f32_16x16x32_bf16 v[30:33], v[164:167], v[180:183], v[30:33]
	v_mfma_f32_16x16x32_bf16 v[26:29], v[168:171], v[180:183], v[26:29]
	s_waitcnt vmcnt(2)
	ds_write_b128 v190, v[236:239] offset:53264
	v_mfma_f32_16x16x32_bf16 v[22:25], v[172:175], v[180:183], v[22:25]
	v_mfma_f32_16x16x32_bf16 v[18:21], v[176:179], v[180:183], v[18:21]
	s_waitcnt vmcnt(1)
	ds_write_b128 v190, v[240:243] offset:57360
	s_waitcnt lgkmcnt(4)
	v_mfma_f32_16x16x32_bf16 v[14:17], v[164:167], v[184:187], v[14:17]
	v_mfma_f32_16x16x32_bf16 v[10:13], v[168:171], v[184:187], v[10:13]
	s_waitcnt vmcnt(0)
	ds_write_b128 v190, v[244:247] offset:61456
	v_mfma_f32_16x16x32_bf16 v[6:9], v[172:175], v[184:187], v[6:9]
	v_mfma_f32_16x16x32_bf16 v[2:5], v[176:179], v[184:187], v[2:5]
	s_waitcnt lgkmcnt(0)
	s_barrier
	ds_read_b128 v[82:85], v71 offset:32768
	ds_read_b128 v[74:77], v188 offset:49168
	ds_read_b128 v[78:81], v188 offset:49680
	ds_read_b128 v[90:93], v188 offset:53264
	ds_read_b128 v[94:97], v188 offset:53776
	ds_read_b128 v[86:89], v71 offset:34816
	s_waitcnt lgkmcnt(4)
	v_mfma_f32_16x16x32_bf16 v[30:33], v[74:77], v[82:85], v[30:33]
	ds_read_b128 v[164:167], v189 offset:49168
	ds_read_b128 v[168:171], v189 offset:49680
	s_waitcnt lgkmcnt(5)
	v_mfma_f32_16x16x32_bf16 v[26:29], v[78:81], v[82:85], v[26:29]
	s_waitcnt lgkmcnt(4)
	v_mfma_f32_16x16x32_bf16 v[22:25], v[90:93], v[82:85], v[22:25]
	ds_read_b128 v[172:175], v189 offset:53264
	ds_read_b128 v[176:179], v189 offset:53776
	s_waitcnt lgkmcnt(5)
	v_mfma_f32_16x16x32_bf16 v[18:21], v[94:97], v[82:85], v[18:21]
	s_waitcnt lgkmcnt(4)
	v_mfma_f32_16x16x32_bf16 v[14:17], v[74:77], v[86:89], v[14:17]
	ds_read_b128 v[180:183], v72 offset:32768
	ds_read_b128 v[184:187], v72 offset:34816
	v_mfma_f32_16x16x32_bf16 v[10:13], v[78:81], v[86:89], v[10:13]
	v_mfma_f32_16x16x32_bf16 v[6:9], v[90:93], v[86:89], v[6:9]
	v_mfma_f32_16x16x32_bf16 v[2:5], v[94:97], v[86:89], v[2:5]
	s_waitcnt lgkmcnt(1)
	v_mfma_f32_16x16x32_bf16 v[30:33], v[164:167], v[180:183], v[30:33]
	v_mfma_f32_16x16x32_bf16 v[26:29], v[168:171], v[180:183], v[26:29]
	v_mfma_f32_16x16x32_bf16 v[22:25], v[172:175], v[180:183], v[22:25]
	v_mfma_f32_16x16x32_bf16 v[18:21], v[176:179], v[180:183], v[18:21]
	s_waitcnt lgkmcnt(0)
	v_mfma_f32_16x16x32_bf16 v[14:17], v[164:167], v[184:187], v[14:17]
	v_mfma_f32_16x16x32_bf16 v[10:13], v[168:171], v[184:187], v[10:13]
	v_mfma_f32_16x16x32_bf16 v[6:9], v[172:175], v[184:187], v[6:9]
	v_mfma_f32_16x16x32_bf16 v[2:5], v[176:179], v[184:187], v[2:5]
	s_barrier

.Lgq_o:
	ds_read_b128 v[118:121], v112
	ds_read_b128 v[114:117], v188 offset:16384
	ds_read_b128 v[122:125], v188 offset:16896
	ds_read_b128 v[126:129], v188 offset:20480
	ds_read_b128 v[156:159], v188 offset:20992
	ds_read_b128 v[160:163], v112 offset:2048
	s_waitcnt lgkmcnt(4)
	v_mfma_f32_16x16x32_bf16 v[94:97], v[114:117], v[118:121], v[94:97]
	global_load_dwordx4 v[2:5], v216, s[10:11] offset:256
	s_waitcnt lgkmcnt(3)
	v_mfma_f32_16x16x32_bf16 v[90:93], v[122:125], v[118:121], v[90:93]
	s_waitcnt vmcnt(8)
	ds_write_b128 v108, v[224:227] offset:32768
	s_waitcnt lgkmcnt(3)
	v_mfma_f32_16x16x32_bf16 v[86:89], v[126:129], v[118:121], v[86:89]
	s_waitcnt lgkmcnt(2)
	v_mfma_f32_16x16x32_bf16 v[82:85], v[156:159], v[118:121], v[82:85]
	global_load_dwordx4 v[6:9], v217, s[10:11] offset:256
	s_waitcnt lgkmcnt(1)
	v_mfma_f32_16x16x32_bf16 v[78:81], v[114:117], v[160:163], v[78:81]
	ds_read_b128 v[180:183], v112 offset:4096
	ds_read_b128 v[184:187], v112 offset:6144
	v_mfma_f32_16x16x32_bf16 v[74:77], v[122:125], v[160:163], v[74:77]
	s_waitcnt vmcnt(8)
	ds_write_b128 v108, v[228:231] offset:36864
	v_mfma_f32_16x16x32_bf16 v[70:73], v[126:129], v[160:163], v[70:73]
	global_load_dwordx4 v[10:13], v218, s[10:11] offset:256
	v_mfma_f32_16x16x32_bf16 v[66:69], v[156:159], v[160:163], v[66:69]
	s_waitcnt lgkmcnt(2)
	v_mfma_f32_16x16x32_bf16 v[62:65], v[114:117], v[180:183], v[62:65]
	ds_read_b128 v[164:167], v189 offset:16384
	ds_read_b128 v[168:171], v189 offset:16896
	v_mfma_f32_16x16x32_bf16 v[58:61], v[122:125], v[180:183], v[58:61]
	global_load_dwordx4 v[14:17], v219, s[10:11] offset:256
	v_mfma_f32_16x16x32_bf16 v[54:57], v[126:129], v[180:183], v[54:57]
	ds_read_b128 v[172:175], v189 offset:20480
	ds_read_b128 v[176:179], v189 offset:20992
	v_mfma_f32_16x16x32_bf16 v[50:53], v[156:159], v[180:183], v[50:53]
	s_waitcnt vmcnt(9)
	ds_write_b128 v108, v[232:235] offset:40960
	s_waitcnt lgkmcnt(6)
	v_mfma_f32_16x16x32_bf16 v[46:49], v[114:117], v[184:187], v[46:49]
	ds_read_b128 v[118:121], v113
	ds_read_b128 v[160:163], v113 offset:2048
	v_mfma_f32_16x16x32_bf16 v[42:45], v[122:125], v[184:187], v[42:45]
	global_load_dwordx4 v[18:21], v216, s[28:29] offset:256
	v_mfma_f32_16x16x32_bf16 v[38:41], v[126:129], v[184:187], v[38:41]
	s_waitcnt vmcnt(9)
	ds_write_b128 v108, v[236:239] offset:45056
	v_mfma_f32_16x16x32_bf16 v[34:37], v[156:159], v[184:187], v[34:37]
	s_waitcnt lgkmcnt(2)
	v_mfma_f32_16x16x32_bf16 v[94:97], v[164:167], v[118:121], v[94:97]
	global_load_dwordx4 v[22:25], v217, s[28:29] offset:256
	v_mfma_f32_16x16x32_bf16 v[90:93], v[168:171], v[118:121], v[90:93]
	s_waitcnt vmcnt(9)
	ds_write_b128 v190, v[240:243] offset:49168
	v_mfma_f32_16x16x32_bf16 v[86:89], v[172:175], v[118:121], v[86:89]
	v_mfma_f32_16x16x32_bf16 v[82:85], v[176:179], v[118:121], v[82:85]
	global_load_dwordx4 v[26:29], v218, s[28:29] offset:256
	s_waitcnt lgkmcnt(2)
	v_mfma_f32_16x16x32_bf16 v[78:81], v[164:167], v[160:163], v[78:81]
	ds_read_b128 v[180:183], v113 offset:4096
	ds_read_b128 v[184:187], v113 offset:6144
	v_mfma_f32_16x16x32_bf16 v[74:77], v[168:171], v[160:163], v[74:77]
	s_waitcnt vmcnt(9)
	ds_write_b128 v190, v[244:247] offset:53264
	v_mfma_f32_16x16x32_bf16 v[70:73], v[172:175], v[160:163], v[70:73]
	global_load_dwordx4 v[30:33], v219, s[28:29] offset:256
	v_mfma_f32_16x16x32_bf16 v[66:69], v[176:179], v[160:163], v[66:69]
	s_waitcnt lgkmcnt(2)
	v_mfma_f32_16x16x32_bf16 v[62:65], v[164:167], v[180:183], v[62:65]
	s_waitcnt vmcnt(9)
	ds_write_b128 v190, v[248:251] offset:57360
	v_mfma_f32_16x16x32_bf16 v[58:61], v[168:171], v[180:183], v[58:61]
	v_mfma_f32_16x16x32_bf16 v[54:57], v[172:175], v[180:183], v[54:57]
	v_mfma_f32_16x16x32_bf16 v[50:53], v[176:179], v[180:183], v[50:53]
	s_waitcnt vmcnt(8)
	ds_write_b128 v190, v[252:255] offset:61456
	s_waitcnt lgkmcnt(3)
	v_mfma_f32_16x16x32_bf16 v[46:49], v[164:167], v[184:187], v[46:49]
	v_mfma_f32_16x16x32_bf16 v[42:45], v[168:171], v[184:187], v[42:45]
	v_mfma_f32_16x16x32_bf16 v[38:41], v[172:175], v[184:187], v[38:41]
	v_mfma_f32_16x16x32_bf16 v[34:37], v[176:179], v[184:187], v[34:37]
	s_waitcnt lgkmcnt(0)
	s_barrier
	s_add_u32 s10, s10, 0x80
	s_addc_u32 s11, s11, 0
	s_add_u32 s28, s28, 0x80
	s_addc_u32 s29, s29, 0
	ds_read_b128 v[118:121], v112 offset:32768
	ds_read_b128 v[114:117], v188 offset:49168
	ds_read_b128 v[122:125], v188 offset:49680
	ds_read_b128 v[126:129], v188 offset:53264
	ds_read_b128 v[156:159], v188 offset:53776
	ds_read_b128 v[160:163], v112 offset:34816
	s_waitcnt lgkmcnt(4)
	v_mfma_f32_16x16x32_bf16 v[94:97], v[114:117], v[118:121], v[94:97]
	global_load_dwordx4 v[224:227], v216, s[10:11] offset:256
	s_waitcnt lgkmcnt(3)
	v_mfma_f32_16x16x32_bf16 v[90:93], v[122:125], v[118:121], v[90:93]
	s_waitcnt vmcnt(8)
	ds_write_b128 v108, v[2:5]
	s_waitcnt lgkmcnt(3)
	v_mfma_f32_16x16x32_bf16 v[86:89], v[126:129], v[118:121], v[86:89]
	s_waitcnt lgkmcnt(2)
	v_mfma_f32_16x16x32_bf16 v[82:85], v[156:159], v[118:121], v[82:85]
	global_load_dwordx4 v[228:231], v217, s[10:11] offset:256
	s_waitcnt lgkmcnt(1)
	v_mfma_f32_16x16x32_bf16 v[78:81], v[114:117], v[160:163], v[78:81]
	ds_read_b128 v[180:183], v112 offset:36864
	ds_read_b128 v[184:187], v112 offset:38912
	v_mfma_f32_16x16x32_bf16 v[74:77], v[122:125], v[160:163], v[74:77]
	s_waitcnt vmcnt(8)
	ds_write_b128 v108, v[6:9] offset:4096
	v_mfma_f32_16x16x32_bf16 v[70:73], v[126:129], v[160:163], v[70:73]
	global_load_dwordx4 v[232:235], v218, s[10:11] offset:256
	v_mfma_f32_16x16x32_bf16 v[66:69], v[156:159], v[160:163], v[66:69]
	s_waitcnt lgkmcnt(2)
	v_mfma_f32_16x16x32_bf16 v[62:65], v[114:117], v[180:183], v[62:65]
	ds_read_b128 v[164:167], v189 offset:49168
	ds_read_b128 v[168:171], v189 offset:49680
	v_mfma_f32_16x16x32_bf16 v[58:61], v[122:125], v[180:183], v[58:61]
	global_load_dwordx4 v[236:239], v219, s[10:11] offset:256
	v_mfma_f32_16x16x32_bf16 v[54:57], v[126:129], v[180:183], v[54:57]
	ds_read_b128 v[172:175], v189 offset:53264
	ds_read_b128 v[176:179], v189 offset:53776
	v_mfma_f32_16x16x32_bf16 v[50:53], v[156:159], v[180:183], v[50:53]
	s_waitcnt vmcnt(9)
	ds_write_b128 v108, v[10:13] offset:8192
	s_waitcnt lgkmcnt(6)
	v_mfma_f32_16x16x32_bf16 v[46:49], v[114:117], v[184:187], v[46:49]
	ds_read_b128 v[118:121], v113 offset:32768
	ds_read_b128 v[160:163], v113 offset:34816
	v_mfma_f32_16x16x32_bf16 v[42:45], v[122:125], v[184:187], v[42:45]
	global_load_dwordx4 v[240:243], v216, s[28:29] offset:256
	v_mfma_f32_16x16x32_bf16 v[38:41], v[126:129], v[184:187], v[38:41]
	s_waitcnt vmcnt(9)
	ds_write_b128 v108, v[14:17] offset:12288
	v_mfma_f32_16x16x32_bf16 v[34:37], v[156:159], v[184:187], v[34:37]
	s_waitcnt lgkmcnt(2)
	v_mfma_f32_16x16x32_bf16 v[94:97], v[164:167], v[118:121], v[94:97]
	global_load_dwordx4 v[244:247], v217, s[28:29] offset:256
	v_mfma_f32_16x16x32_bf16 v[90:93], v[168:171], v[118:121], v[90:93]
	s_waitcnt vmcnt(9)
	ds_write_b128 v190, v[18:21] offset:16384
	v_mfma_f32_16x16x32_bf16 v[86:89], v[172:175], v[118:121], v[86:89]
	v_mfma_f32_16x16x32_bf16 v[82:85], v[176:179], v[118:121], v[82:85]
	global_load_dwordx4 v[248:251], v218, s[28:29] offset:256
	s_waitcnt lgkmcnt(2)
	v_mfma_f32_16x16x32_bf16 v[78:81], v[164:167], v[160:163], v[78:81]
	ds_read_b128 v[180:183], v113 offset:36864
	ds_read_b128 v[184:187], v113 offset:38912
	v_mfma_f32_16x16x32_bf16 v[74:77], v[168:171], v[160:163], v[74:77]
	s_waitcnt vmcnt(9)
	ds_write_b128 v190, v[22:25] offset:20480
	v_mfma_f32_16x16x32_bf16 v[70:73], v[172:175], v[160:163], v[70:73]
	global_load_dwordx4 v[252:255], v219, s[28:29] offset:256
	v_mfma_f32_16x16x32_bf16 v[66:69], v[176:179], v[160:163], v[66:69]
	s_waitcnt lgkmcnt(2)
	v_mfma_f32_16x16x32_bf16 v[62:65], v[164:167], v[180:183], v[62:65]
	s_waitcnt vmcnt(9)
	ds_write_b128 v190, v[26:29] offset:24576
	v_mfma_f32_16x16x32_bf16 v[58:61], v[168:171], v[180:183], v[58:61]
	v_mfma_f32_16x16x32_bf16 v[54:57], v[172:175], v[180:183], v[54:57]
	v_mfma_f32_16x16x32_bf16 v[50:53], v[176:179], v[180:183], v[50:53]
	s_waitcnt vmcnt(8)
	ds_write_b128 v190, v[30:33] offset:28672
	s_waitcnt lgkmcnt(3)
	v_mfma_f32_16x16x32_bf16 v[46:49], v[164:167], v[184:187], v[46:49]
	v_mfma_f32_16x16x32_bf16 v[42:45], v[168:171], v[184:187], v[42:45]
	v_mfma_f32_16x16x32_bf16 v[38:41], v[172:175], v[184:187], v[38:41]
	v_mfma_f32_16x16x32_bf16 v[34:37], v[176:179], v[184:187], v[34:37]
	s_waitcnt lgkmcnt(0)
	s_barrier
	s_add_u32 s10, s10, 0x80
	s_addc_u32 s11, s11, 0
	s_add_u32 s28, s28, 0x80
	s_addc_u32 s29, s29, 0
	s_sub_i32 vcc_lo, vcc_lo, 1
	s_cmp_lg_u32 vcc_lo, 0
	s_cbranch_scc1 .Lgq_o
	ds_read_b128 v[118:121], v112
	ds_read_b128 v[114:117], v188 offset:16384
	ds_read_b128 v[122:125], v188 offset:16896
	ds_read_b128 v[126:129], v188 offset:20480
	ds_read_b128 v[156:159], v188 offset:20992
	ds_read_b128 v[160:163], v112 offset:2048
	s_waitcnt lgkmcnt(4)
	v_mfma_f32_16x16x32_bf16 v[94:97], v[114:117], v[118:121], v[94:97]
	s_waitcnt lgkmcnt(3)
	v_mfma_f32_16x16x32_bf16 v[90:93], v[122:125], v[118:121], v[90:93]
	s_waitcnt vmcnt(7)
	ds_write_b128 v108, v[224:227] offset:32768
	s_waitcnt lgkmcnt(3)
	v_mfma_f32_16x16x32_bf16 v[86:89], v[126:129], v[118:121], v[86:89]
	s_waitcnt lgkmcnt(2)
	v_mfma_f32_16x16x32_bf16 v[82:85], v[156:159], v[118:121], v[82:85]
	s_waitcnt lgkmcnt(1)
	v_mfma_f32_16x16x32_bf16 v[78:81], v[114:117], v[160:163], v[78:81]
	ds_read_b128 v[180:183], v112 offset:4096
	ds_read_b128 v[184:187], v112 offset:6144
	v_mfma_f32_16x16x32_bf16 v[74:77], v[122:125], v[160:163], v[74:77]
	s_waitcnt vmcnt(6)
	ds_write_b128 v108, v[228:231] offset:36864
	v_mfma_f32_16x16x32_bf16 v[70:73], v[126:129], v[160:163], v[70:73]
	v_mfma_f32_16x16x32_bf16 v[66:69], v[156:159], v[160:163], v[66:69]
	s_waitcnt lgkmcnt(2)
	v_mfma_f32_16x16x32_bf16 v[62:65], v[114:117], v[180:183], v[62:65]
	ds_read_b128 v[164:167], v189 offset:16384
	ds_read_b128 v[168:171], v189 offset:16896
	v_mfma_f32_16x16x32_bf16 v[58:61], v[122:125], v[180:183], v[58:61]
	v_mfma_f32_16x16x32_bf16 v[54:57], v[126:129], v[180:183], v[54:57]
	ds_read_b128 v[172:175], v189 offset:20480
	ds_read_b128 v[176:179], v189 offset:20992
	v_mfma_f32_16x16x32_bf16 v[50:53], v[156:159], v[180:183], v[50:53]
	s_waitcnt vmcnt(5)
	ds_write_b128 v108, v[232:235] offset:40960
	s_waitcnt lgkmcnt(6)
	v_mfma_f32_16x16x32_bf16 v[46:49], v[114:117], v[184:187], v[46:49]
	ds_read_b128 v[118:121], v113
	ds_read_b128 v[160:163], v113 offset:2048
	v_mfma_f32_16x16x32_bf16 v[42:45], v[122:125], v[184:187], v[42:45]
	v_mfma_f32_16x16x32_bf16 v[38:41], v[126:129], v[184:187], v[38:41]
	s_waitcnt vmcnt(4)
	ds_write_b128 v108, v[236:239] offset:45056
	v_mfma_f32_16x16x32_bf16 v[34:37], v[156:159], v[184:187], v[34:37]
	s_waitcnt lgkmcnt(2)
	v_mfma_f32_16x16x32_bf16 v[94:97], v[164:167], v[118:121], v[94:97]
	v_mfma_f32_16x16x32_bf16 v[90:93], v[168:171], v[118:121], v[90:93]
	s_waitcnt vmcnt(3)
	ds_write_b128 v190, v[240:243] offset:49168
	v_mfma_f32_16x16x32_bf16 v[86:89], v[172:175], v[118:121], v[86:89]
	v_mfma_f32_16x16x32_bf16 v[82:85], v[176:179], v[118:121], v[82:85]
	s_waitcnt lgkmcnt(2)
	v_mfma_f32_16x16x32_bf16 v[78:81], v[164:167], v[160:163], v[78:81]
	ds_read_b128 v[180:183], v113 offset:4096
	ds_read_b128 v[184:187], v113 offset:6144
	v_mfma_f32_16x16x32_bf16 v[74:77], v[168:171], v[160:163], v[74:77]
	s_waitcnt vmcnt(2)
	ds_write_b128 v190, v[244:247] offset:53264
	v_mfma_f32_16x16x32_bf16 v[70:73], v[172:175], v[160:163], v[70:73]
	v_mfma_f32_16x16x32_bf16 v[66:69], v[176:179], v[160:163], v[66:69]
	s_waitcnt lgkmcnt(2)
	v_mfma_f32_16x16x32_bf16 v[62:65], v[164:167], v[180:183], v[62:65]
	s_waitcnt vmcnt(1)
	ds_write_b128 v190, v[248:251] offset:57360
	v_mfma_f32_16x16x32_bf16 v[58:61], v[168:171], v[180:183], v[58:61]
	v_mfma_f32_16x16x32_bf16 v[54:57], v[172:175], v[180:183], v[54:57]
	v_mfma_f32_16x16x32_bf16 v[50:53], v[176:179], v[180:183], v[50:53]
	s_waitcnt vmcnt(0)
	ds_write_b128 v190, v[252:255] offset:61456
	s_waitcnt lgkmcnt(3)
	v_mfma_f32_16x16x32_bf16 v[46:49], v[164:167], v[184:187], v[46:49]
	v_mfma_f32_16x16x32_bf16 v[42:45], v[168:171], v[184:187], v[42:45]
	v_mfma_f32_16x16x32_bf16 v[38:41], v[172:175], v[184:187], v[38:41]
	v_mfma_f32_16x16x32_bf16 v[34:37], v[176:179], v[184:187], v[34:37]
	s_waitcnt lgkmcnt(0)
	s_barrier
	ds_read_b128 v[118:121], v112 offset:32768
	ds_read_b128 v[114:117], v188 offset:49168
	ds_read_b128 v[122:125], v188 offset:49680
	ds_read_b128 v[126:129], v188 offset:53264
	ds_read_b128 v[156:159], v188 offset:53776
	ds_read_b128 v[160:163], v112 offset:34816
	s_waitcnt lgkmcnt(4)
	v_mfma_f32_16x16x32_bf16 v[94:97], v[114:117], v[118:121], v[94:97]
	s_waitcnt lgkmcnt(3)
	v_mfma_f32_16x16x32_bf16 v[90:93], v[122:125], v[118:121], v[90:93]
	s_waitcnt lgkmcnt(2)
	v_mfma_f32_16x16x32_bf16 v[86:89], v[126:129], v[118:121], v[86:89]
	s_waitcnt lgkmcnt(1)
	v_mfma_f32_16x16x32_bf16 v[82:85], v[156:159], v[118:121], v[82:85]
	s_waitcnt lgkmcnt(0)
	v_mfma_f32_16x16x32_bf16 v[78:81], v[114:117], v[160:163], v[78:81]
	ds_read_b128 v[180:183], v112 offset:36864
	ds_read_b128 v[184:187], v112 offset:38912
	v_mfma_f32_16x16x32_bf16 v[74:77], v[122:125], v[160:163], v[74:77]
	v_mfma_f32_16x16x32_bf16 v[70:73], v[126:129], v[160:163], v[70:73]
	v_mfma_f32_16x16x32_bf16 v[66:69], v[156:159], v[160:163], v[66:69]
	s_waitcnt lgkmcnt(1)
	v_mfma_f32_16x16x32_bf16 v[62:65], v[114:117], v[180:183], v[62:65]
	ds_read_b128 v[164:167], v189 offset:49168
	ds_read_b128 v[168:171], v189 offset:49680
	v_mfma_f32_16x16x32_bf16 v[58:61], v[122:125], v[180:183], v[58:61]
	v_mfma_f32_16x16x32_bf16 v[54:57], v[126:129], v[180:183], v[54:57]
	ds_read_b128 v[172:175], v189 offset:53264
	ds_read_b128 v[176:179], v189 offset:53776
	v_mfma_f32_16x16x32_bf16 v[50:53], v[156:159], v[180:183], v[50:53]
	s_waitcnt lgkmcnt(4)
	v_mfma_f32_16x16x32_bf16 v[46:49], v[114:117], v[184:187], v[46:49]
	ds_read_b128 v[118:121], v113 offset:32768
	ds_read_b128 v[160:163], v113 offset:34816
	v_mfma_f32_16x16x32_bf16 v[42:45], v[122:125], v[184:187], v[42:45]
	v_mfma_f32_16x16x32_bf16 v[38:41], v[126:129], v[184:187], v[38:41]
	v_mfma_f32_16x16x32_bf16 v[34:37], v[156:159], v[184:187], v[34:37]
	s_waitcnt lgkmcnt(1)
	v_mfma_f32_16x16x32_bf16 v[94:97], v[164:167], v[118:121], v[94:97]
	v_mfma_f32_16x16x32_bf16 v[90:93], v[168:171], v[118:121], v[90:93]
	v_mfma_f32_16x16x32_bf16 v[86:89], v[172:175], v[118:121], v[86:89]
	v_mfma_f32_16x16x32_bf16 v[82:85], v[176:179], v[118:121], v[82:85]
	s_waitcnt lgkmcnt(0)
	v_mfma_f32_16x16x32_bf16 v[78:81], v[164:167], v[160:163], v[78:81]
	ds_read_b128 v[180:183], v113 offset:36864
	ds_read_b128 v[184:187], v113 offset:38912
	v_mfma_f32_16x16x32_bf16 v[74:77], v[168:171], v[160:163], v[74:77]
	v_mfma_f32_16x16x32_bf16 v[70:73], v[172:175], v[160:163], v[70:73]
	v_mfma_f32_16x16x32_bf16 v[66:69], v[176:179], v[160:163], v[66:69]
	s_waitcnt lgkmcnt(1)
	v_mfma_f32_16x16x32_bf16 v[62:65], v[164:167], v[180:183], v[62:65]
	v_mfma_f32_16x16x32_bf16 v[58:61], v[168:171], v[180:183], v[58:61]
	v_mfma_f32_16x16x32_bf16 v[54:57], v[172:175], v[180:183], v[54:57]
	v_mfma_f32_16x16x32_bf16 v[50:53], v[176:179], v[180:183], v[50:53]
	s_waitcnt lgkmcnt(0)
	v_mfma_f32_16x16x32_bf16 v[46:49], v[164:167], v[184:187], v[46:49]
	v_mfma_f32_16x16x32_bf16 v[42:45], v[168:171], v[184:187], v[42:45]
	v_mfma_f32_16x16x32_bf16 v[38:41], v[172:175], v[184:187], v[38:41]
	v_mfma_f32_16x16x32_bf16 v[34:37], v[176:179], v[184:187], v[34:37]
	s_barrier
	s_branch .LBB0_1383
